# speedup vs baseline: 1.0096x; 1.0001x over previous
; #define MFMA32(a, b, c) __builtin_amdgcn_mfma_f32_32x32x16_bf16((a), (b), (c), 0, 0, 0)
; #define TK_PREFETCH(t_, p_) do { const int tk0_ = ((t_) >> 3) * 64, hp_ = ((t_) & 7) * 2 + (p_); \
;         _Pragma("unroll") for (int i_ = 0; i_ < 4; ++i_) { const int c_ = tid + 256 * i_; pre[i_] = *(const u32x4*)(qp + (size_t)(tk0_ + (c_ >> 4)) * 2048 + hp_ * 128 + (c_ & 15) * 8); } } while (0)
; DI void topk_phase(unsigned char* smem_, const bf16_t* __restrict__ qp, const bf16_t* __restrict__ keys, int* __restrict__ eidx, float* __restrict__ gate) {
;     ...
;     for (int p = 0; p < 2; ++p) {
; #pragma unroll
;         for (int i = 0; i < 4; ++i) { const int c = tid + 256 * i; *(u32x4*)(As + (c >> 4) * LDA + (c & 15) * 8) = pre[i]; }
;         __syncthreads();
;         f32x16 acc[2];
; #pragma unroll
;         for (int i = 0; i < 16; ++i) { acc[0][i] = 0.f; acc[1][i] = 0.f; }
; #pragma unroll
;         for (int ks = 0; ks < 8; ++ks) {
; #pragma unroll
;             for (int th = 0; th < 2; ++th) { const bf16x8 qf = *(const bf16x8*)(As + (32 * th + l31) * LDA + ks * 16 + hi * 8); acc[th] = MFMA32(kf[p][ks], qf, acc[th]); }
;         }
; #pragma unroll
;         for (int th = 0; th < 2; ++th)
; #pragma unroll
;             for (int g = 0; g < 4; ++g) { f32x4 o; o.x = acc[th][4 * g]; o.y = acc[th][4 * g + 1]; o.z = acc[th][4 * g + 2]; o.w = acc[th][4 * g + 3]; *(f32x4*)(S + (32 * th + l31) * LDS_ + 32 * wid + 8 * g + 4 * hi) = o; }
;         __syncthreads();
;         if (p == 0) TK_PREFETCH(t, 1); else if (t + G < NT) TK_PREFETCH(t + G, 0);
;         unsigned v[32];
; #pragma unroll
;         for (int i = 0; i < 8; ++i) {
;             const f32x4 sv4 = *(const f32x4*)(S + row * LDS_ + 32 * q + 4 * i);
.LBB0_57:
	s_waitcnt vmcnt(0)
	ds_write_b128 v234, v[96:99]
	ds_write_b128 v234, v[100:103] offset:4352
	ds_write_b128 v234, v[104:107] offset:8704
	ds_write_b128 v234, v[108:111] offset:13056
	s_waitcnt lgkmcnt(0)
	s_barrier
	ds_read_b128 v[0:3], v235
	ds_read_b128 v[96:99], v235 offset:32
	s_waitcnt lgkmcnt(1)
	v_mfma_f32_32x32x16_bf16 v[16:31], v[32:35], v[0:3], 0
	ds_read_b128 v[0:3], v235 offset:8704
	s_and_b32 s24, s22, 0xffffffc0
	s_lshl_b32 s0, s0, 1
	s_add_u32 s0, s86, s0
	s_addc_u32 s1, s87, 0
	s_waitcnt lgkmcnt(1)
	v_mfma_f32_32x32x16_bf16 v[16:31], v[36:39], v[96:99], v[16:31]
	ds_read_b128 v[96:99], v235 offset:8736
	s_waitcnt lgkmcnt(1)
	v_mfma_f32_32x32x16_bf16 v[0:15], v[32:35], v[0:3], 0
	s_waitcnt lgkmcnt(0)
	v_mfma_f32_32x32x16_bf16 v[0:15], v[36:39], v[96:99], v[0:15]
	ds_read_b128 v[100:103], v235 offset:64
	ds_read_b128 v[104:107], v235 offset:8768
	ds_read_b128 v[108:111], v235 offset:96
	s_waitcnt lgkmcnt(2)
	v_mfma_f32_32x32x16_bf16 v[16:31], v[40:43], v[100:103], v[16:31]
	ds_read_b128 v[96:99], v235 offset:8800
	s_waitcnt lgkmcnt(2)
	v_mfma_f32_32x32x16_bf16 v[0:15], v[40:43], v[104:107], v[0:15]
	ds_read_b128 v[100:103], v235 offset:128
	s_waitcnt lgkmcnt(2)
	v_mfma_f32_32x32x16_bf16 v[16:31], v[44:47], v[108:111], v[16:31]
	ds_read_b128 v[104:107], v235 offset:8832
	s_waitcnt lgkmcnt(2)
	v_mfma_f32_32x32x16_bf16 v[0:15], v[44:47], v[96:99], v[0:15]
	ds_read_b128 v[108:111], v235 offset:160
	s_waitcnt lgkmcnt(2)
	v_mfma_f32_32x32x16_bf16 v[16:31], v[48:51], v[100:103], v[16:31]
	ds_read_b128 v[96:99], v235 offset:8864
	s_waitcnt lgkmcnt(2)
	v_mfma_f32_32x32x16_bf16 v[0:15], v[48:51], v[104:107], v[0:15]
	ds_read_b128 v[100:103], v235 offset:192
	s_waitcnt lgkmcnt(2)
	v_mfma_f32_32x32x16_bf16 v[16:31], v[52:55], v[108:111], v[16:31]
	ds_read_b128 v[104:107], v235 offset:8896
	s_waitcnt lgkmcnt(2)
	v_mfma_f32_32x32x16_bf16 v[0:15], v[52:55], v[96:99], v[0:15]
	ds_read_b128 v[108:111], v235 offset:224
	s_waitcnt lgkmcnt(2)
	v_mfma_f32_32x32x16_bf16 v[16:31], v[56:59], v[100:103], v[16:31]
	ds_read_b128 v[96:99], v235 offset:8928
	s_waitcnt lgkmcnt(2)
	v_mfma_f32_32x32x16_bf16 v[0:15], v[56:59], v[104:107], v[0:15]
	s_waitcnt lgkmcnt(1)
	v_mfma_f32_32x32x16_bf16 v[16:31], v[60:63], v[108:111], v[16:31]
	s_nop 0
	s_nop 10
	ds_write_b128 v236, v[16:19] offset:17408
	ds_write_b128 v236, v[20:23] offset:17440
	ds_write_b128 v236, v[24:27] offset:17472
	ds_write_b128 v236, v[28:31] offset:17504
	s_waitcnt lgkmcnt(4)
	v_mfma_f32_32x32x16_bf16 v[0:15], v[60:63], v[96:99], v[0:15]
	s_nop 11
	ds_write_b128 v236, v[0:3] offset:34304
	ds_write_b128 v236, v[4:7] offset:34336
	ds_write_b128 v236, v[8:11] offset:34368
	ds_write_b128 v236, v[12:15] offset:34400
	v_or_b32_e32 v0, s24, v165
	v_ashrrev_i32_e32 v1, 31, v0
	v_lshlrev_b64 v[0:1], 12, v[0:1]
	v_lshl_add_u64 v[0:1], s[0:1], 0, v[0:1]
	v_lshl_add_u64 v[0:1], v[0:1], 0, v[128:129]
	s_waitcnt lgkmcnt(0)
	s_barrier
	global_load_dwordx4 v[96:99], v[0:1], off offset:256
	v_or_b32_e32 v0, s24, v166
	v_ashrrev_i32_e32 v1, 31, v0
	v_lshlrev_b64 v[0:1], 12, v[0:1]
	v_lshl_add_u64 v[0:1], s[0:1], 0, v[0:1]
	v_lshl_add_u64 v[0:1], v[0:1], 0, v[128:129]
	global_load_dwordx4 v[100:103], v[0:1], off offset:256
	v_or_b32_e32 v0, s24, v167
	v_ashrrev_i32_e32 v1, 31, v0
	v_lshlrev_b64 v[0:1], 12, v[0:1]
	v_lshl_add_u64 v[0:1], s[0:1], 0, v[0:1]
	v_lshl_add_u64 v[0:1], v[0:1], 0, v[128:129]
	global_load_dwordx4 v[104:107], v[0:1], off offset:256
	v_or_b32_e32 v0, s24, v168
	v_ashrrev_i32_e32 v1, 31, v0
	v_lshlrev_b64 v[0:1], 12, v[0:1]
	v_lshl_add_u64 v[0:1], s[0:1], 0, v[0:1]
	v_lshl_add_u64 v[4:5], v[0:1], 0, v[128:129]
	ds_read_b128 v[0:3], v171 offset:17408
	global_load_dwordx4 v[108:111], v[4:5], off offset:256
	ds_read_b128 v[4:7], v171 offset:17424
	ds_read_b128 v[8:11], v171 offset:17440
	ds_read_b128 v[12:15], v171 offset:17456
	s_waitcnt lgkmcnt(3)
	v_ashrrev_i32_e32 v16, 31, v0


; DI unsigned fkey(float f) { const unsigned u = __float_as_uint(f); return (u & 0x80000000u) ? ~u : (u | 0x80000000u); }
; DI void topk_phase(unsigned char* smem_, const bf16_t* __restrict__ qp, const bf16_t* __restrict__ keys, int* __restrict__ eidx, float* __restrict__ gate) {
;     ...
;         for (int i = 0; i < 8; ++i) {
;             const f32x4 sv4 = *(const f32x4*)(S + row * LDS_ + 32 * q + 4 * i);
;             const int ib = 127 - (32 * q + 4 * i);
;             v[4 * i] = (fkey(sv4.x) & ~127u) | (unsigned)ib; v[4 * i + 1] = (fkey(sv4.y) & ~127u) | (unsigned)(ib - 1);
;             v[4 * i + 2] = (fkey(sv4.z) & ~127u) | (unsigned)(ib - 2); v[4 * i + 3] = (fkey(sv4.w) & ~127u) | (unsigned)(ib - 3);
;         }
	s_waitcnt lgkmcnt(0)
	v_not_b32_e32 v20, v15
	v_or_b32_e32 v21, 0x80000000, v15
	v_bitop3_b32 v0, v16, s98, v0 bitop3:0x56
	v_ashrrev_i32_e32 v16, 31, v1


; DI unsigned fkey(float f) { const unsigned u = __float_as_uint(f); return (u & 0x80000000u) ? ~u : (u | 0x80000000u); }
; DI void topk_phase(unsigned char* smem_, const bf16_t* __restrict__ qp, const bf16_t* __restrict__ keys, int* __restrict__ eidx, float* __restrict__ gate) {
;     ...
;         for (int i = 0; i < 8; ++i) {
;             const f32x4 sv4 = *(const f32x4*)(S + row * LDS_ + 32 * q + 4 * i);
;             const int ib = 127 - (32 * q + 4 * i);
;             v[4 * i] = (fkey(sv4.x) & ~127u) | (unsigned)ib; v[4 * i + 1] = (fkey(sv4.y) & ~127u) | (unsigned)(ib - 1);
;             v[4 * i + 2] = (fkey(sv4.z) & ~127u) | (unsigned)(ib - 2); v[4 * i + 3] = (fkey(sv4.w) & ~127u) | (unsigned)(ib - 3);
;         }
	v_and_b32_e32 v0, 0xffffff80, v0
	v_sub_u32_e32 v0, v0, v170
	v_bitop3_b32 v1, v16, s98, v1 bitop3:0x56
	v_ashrrev_i32_e32 v16, 31, v2


; DI unsigned fkey(float f) { const unsigned u = __float_as_uint(f); return (u & 0x80000000u) ? ~u : (u | 0x80000000u); }
; DI void topk_phase(unsigned char* smem_, const bf16_t* __restrict__ qp, const bf16_t* __restrict__ keys, int* __restrict__ eidx, float* __restrict__ gate) {
;     ...
;         for (int i = 0; i < 8; ++i) {
;             const f32x4 sv4 = *(const f32x4*)(S + row * LDS_ + 32 * q + 4 * i);
;             const int ib = 127 - (32 * q + 4 * i);
;             v[4 * i] = (fkey(sv4.x) & ~127u) | (unsigned)ib; v[4 * i + 1] = (fkey(sv4.y) & ~127u) | (unsigned)(ib - 1);
;             v[4 * i + 2] = (fkey(sv4.z) & ~127u) | (unsigned)(ib - 2); v[4 * i + 3] = (fkey(sv4.w) & ~127u) | (unsigned)(ib - 3);
;         }
	v_and_b32_e32 v1, 0xffffff80, v1
	v_sub_u32_e32 v1, v1, v170
	v_bitop3_b32 v2, v16, s98, v2 bitop3:0x56
	v_ashrrev_i32_e32 v16, 31, v3


; DI unsigned fkey(float f) { const unsigned u = __float_as_uint(f); return (u & 0x80000000u) ? ~u : (u | 0x80000000u); }
; DI void topk_phase(unsigned char* smem_, const bf16_t* __restrict__ qp, const bf16_t* __restrict__ keys, int* __restrict__ eidx, float* __restrict__ gate) {
;     ...
;         for (int i = 0; i < 8; ++i) {
;             const f32x4 sv4 = *(const f32x4*)(S + row * LDS_ + 32 * q + 4 * i);
;             const int ib = 127 - (32 * q + 4 * i);
;             v[4 * i] = (fkey(sv4.x) & ~127u) | (unsigned)ib; v[4 * i + 1] = (fkey(sv4.y) & ~127u) | (unsigned)(ib - 1);
;             v[4 * i + 2] = (fkey(sv4.z) & ~127u) | (unsigned)(ib - 2); v[4 * i + 3] = (fkey(sv4.w) & ~127u) | (unsigned)(ib - 3);
;         }
	v_and_b32_e32 v2, 0xffffff80, v2
	v_sub_u32_e32 v2, v2, v170
	v_bitop3_b32 v3, v16, s98, v3 bitop3:0x56
	v_ashrrev_i32_e32 v16, 31, v4


; DI unsigned fkey(float f) { const unsigned u = __float_as_uint(f); return (u & 0x80000000u) ? ~u : (u | 0x80000000u); }
; DI void topk_phase(unsigned char* smem_, const bf16_t* __restrict__ qp, const bf16_t* __restrict__ keys, int* __restrict__ eidx, float* __restrict__ gate) {
;     ...
;         for (int i = 0; i < 8; ++i) {
;             const f32x4 sv4 = *(const f32x4*)(S + row * LDS_ + 32 * q + 4 * i);
;             const int ib = 127 - (32 * q + 4 * i);
;             v[4 * i] = (fkey(sv4.x) & ~127u) | (unsigned)ib; v[4 * i + 1] = (fkey(sv4.y) & ~127u) | (unsigned)(ib - 1);
;             v[4 * i + 2] = (fkey(sv4.z) & ~127u) | (unsigned)(ib - 2); v[4 * i + 3] = (fkey(sv4.w) & ~127u) | (unsigned)(ib - 3);
;         }
	v_and_b32_e32 v3, 0xffffff80, v3
	v_sub_u32_e32 v3, v3, v170
	v_bitop3_b32 v4, v16, s98, v4 bitop3:0x56
	v_ashrrev_i32_e32 v16, 31, v5


; DI unsigned fkey(float f) { const unsigned u = __float_as_uint(f); return (u & 0x80000000u) ? ~u : (u | 0x80000000u); }
; DI void topk_phase(unsigned char* smem_, const bf16_t* __restrict__ qp, const bf16_t* __restrict__ keys, int* __restrict__ eidx, float* __restrict__ gate) {
;     ...
;         for (int i = 0; i < 8; ++i) {
;             const f32x4 sv4 = *(const f32x4*)(S + row * LDS_ + 32 * q + 4 * i);
;             const int ib = 127 - (32 * q + 4 * i);
;             v[4 * i] = (fkey(sv4.x) & ~127u) | (unsigned)ib; v[4 * i + 1] = (fkey(sv4.y) & ~127u) | (unsigned)(ib - 1);
;             v[4 * i + 2] = (fkey(sv4.z) & ~127u) | (unsigned)(ib - 2); v[4 * i + 3] = (fkey(sv4.w) & ~127u) | (unsigned)(ib - 3);
;         }
	v_and_b32_e32 v4, 0xffffff80, v4
	v_sub_u32_e32 v4, v4, v177
	v_bitop3_b32 v5, v16, s98, v5 bitop3:0x56
	v_ashrrev_i32_e32 v16, 31, v6


; DI unsigned fkey(float f) { const unsigned u = __float_as_uint(f); return (u & 0x80000000u) ? ~u : (u | 0x80000000u); }
; DI void topk_phase(unsigned char* smem_, const bf16_t* __restrict__ qp, const bf16_t* __restrict__ keys, int* __restrict__ eidx, float* __restrict__ gate) {
;     ...
;         for (int i = 0; i < 8; ++i) {
;             const f32x4 sv4 = *(const f32x4*)(S + row * LDS_ + 32 * q + 4 * i);
;             const int ib = 127 - (32 * q + 4 * i);
;             v[4 * i] = (fkey(sv4.x) & ~127u) | (unsigned)ib; v[4 * i + 1] = (fkey(sv4.y) & ~127u) | (unsigned)(ib - 1);
;             v[4 * i + 2] = (fkey(sv4.z) & ~127u) | (unsigned)(ib - 2); v[4 * i + 3] = (fkey(sv4.w) & ~127u) | (unsigned)(ib - 3);
;         }
	v_and_b32_e32 v5, 0xffffff80, v5
	v_sub_u32_e32 v5, v5, v177
	v_bitop3_b32 v6, v16, s98, v6 bitop3:0x56
	v_ashrrev_i32_e32 v16, 31, v7


; DI unsigned fkey(float f) { const unsigned u = __float_as_uint(f); return (u & 0x80000000u) ? ~u : (u | 0x80000000u); }
; DI void topk_phase(unsigned char* smem_, const bf16_t* __restrict__ qp, const bf16_t* __restrict__ keys, int* __restrict__ eidx, float* __restrict__ gate) {
;     ...
;         for (int i = 0; i < 8; ++i) {
;             const f32x4 sv4 = *(const f32x4*)(S + row * LDS_ + 32 * q + 4 * i);
;             const int ib = 127 - (32 * q + 4 * i);
;             v[4 * i] = (fkey(sv4.x) & ~127u) | (unsigned)ib; v[4 * i + 1] = (fkey(sv4.y) & ~127u) | (unsigned)(ib - 1);
;             v[4 * i + 2] = (fkey(sv4.z) & ~127u) | (unsigned)(ib - 2); v[4 * i + 3] = (fkey(sv4.w) & ~127u) | (unsigned)(ib - 3);
;         }
	v_and_b32_e32 v6, 0xffffff80, v6
	v_sub_u32_e32 v6, v6, v177
	v_bitop3_b32 v7, v16, s98, v7 bitop3:0x56
	v_ashrrev_i32_e32 v16, 31, v8


; DI unsigned fkey(float f) { const unsigned u = __float_as_uint(f); return (u & 0x80000000u) ? ~u : (u | 0x80000000u); }
; DI void topk_phase(unsigned char* smem_, const bf16_t* __restrict__ qp, const bf16_t* __restrict__ keys, int* __restrict__ eidx, float* __restrict__ gate) {
;     ...
;         for (int i = 0; i < 8; ++i) {
;             const f32x4 sv4 = *(const f32x4*)(S + row * LDS_ + 32 * q + 4 * i);
;             const int ib = 127 - (32 * q + 4 * i);
;             v[4 * i] = (fkey(sv4.x) & ~127u) | (unsigned)ib; v[4 * i + 1] = (fkey(sv4.y) & ~127u) | (unsigned)(ib - 1);
;             v[4 * i + 2] = (fkey(sv4.z) & ~127u) | (unsigned)(ib - 2); v[4 * i + 3] = (fkey(sv4.w) & ~127u) | (unsigned)(ib - 3);
;         }
	v_and_b32_e32 v7, 0xffffff80, v7
	v_sub_u32_e32 v7, v7, v177
	v_bitop3_b32 v8, v16, s98, v8 bitop3:0x56
	v_ashrrev_i32_e32 v16, 31, v9


; DI unsigned fkey(float f) { const unsigned u = __float_as_uint(f); return (u & 0x80000000u) ? ~u : (u | 0x80000000u); }
; DI void topk_phase(unsigned char* smem_, const bf16_t* __restrict__ qp, const bf16_t* __restrict__ keys, int* __restrict__ eidx, float* __restrict__ gate) {
;     ...
;         for (int i = 0; i < 8; ++i) {
;             const f32x4 sv4 = *(const f32x4*)(S + row * LDS_ + 32 * q + 4 * i);
;             const int ib = 127 - (32 * q + 4 * i);
;             v[4 * i] = (fkey(sv4.x) & ~127u) | (unsigned)ib; v[4 * i + 1] = (fkey(sv4.y) & ~127u) | (unsigned)(ib - 1);
;             v[4 * i + 2] = (fkey(sv4.z) & ~127u) | (unsigned)(ib - 2); v[4 * i + 3] = (fkey(sv4.w) & ~127u) | (unsigned)(ib - 3);
;         }
	v_and_b32_e32 v8, 0xffffff80, v8
	v_sub_u32_e32 v8, v8, v178
	v_bitop3_b32 v9, v16, s98, v9 bitop3:0x56
	v_ashrrev_i32_e32 v16, 31, v10


; DI unsigned fkey(float f) { const unsigned u = __float_as_uint(f); return (u & 0x80000000u) ? ~u : (u | 0x80000000u); }
; DI void topk_phase(unsigned char* smem_, const bf16_t* __restrict__ qp, const bf16_t* __restrict__ keys, int* __restrict__ eidx, float* __restrict__ gate) {
;     ...
;         for (int i = 0; i < 8; ++i) {
;             const f32x4 sv4 = *(const f32x4*)(S + row * LDS_ + 32 * q + 4 * i);
;             const int ib = 127 - (32 * q + 4 * i);
;             v[4 * i] = (fkey(sv4.x) & ~127u) | (unsigned)ib; v[4 * i + 1] = (fkey(sv4.y) & ~127u) | (unsigned)(ib - 1);
;             v[4 * i + 2] = (fkey(sv4.z) & ~127u) | (unsigned)(ib - 2); v[4 * i + 3] = (fkey(sv4.w) & ~127u) | (unsigned)(ib - 3);
;         }
	v_and_b32_e32 v9, 0xffffff80, v9
	v_sub_u32_e32 v9, v9, v178
	v_bitop3_b32 v10, v16, s98, v10 bitop3:0x56
	v_and_b32_e32 v10, 0xffffff80, v10
	v_sub_u32_e32 v10, v10, v178
	v_add_u32_e32 v16, 0x7d, v10
	v_not_b32_e32 v10, v11
	v_or_b32_e32 v17, 0x80000000, v11
	v_cmp_gt_i32_e32 vcc, 0, v11
	v_ashrrev_i32_e32 v11, 31, v12
	v_add_u32_e32 v0, 0x7f, v0
	v_cndmask_b32_e32 v10, v17, v10, vcc
	v_and_b32_e32 v10, 0xffffff80, v10
	v_sub_u32_e32 v10, v10, v178
	v_add_u32_e32 v17, 0x7c, v10


; DI unsigned fkey(float f) { const unsigned u = __float_as_uint(f); return (u & 0x80000000u) ? ~u : (u | 0x80000000u); }
; DI void topk_phase(unsigned char* smem_, const bf16_t* __restrict__ qp, const bf16_t* __restrict__ keys, int* __restrict__ eidx, float* __restrict__ gate) {
;     ...
;         for (int i = 0; i < 8; ++i) {
;             const f32x4 sv4 = *(const f32x4*)(S + row * LDS_ + 32 * q + 4 * i);
;             const int ib = 127 - (32 * q + 4 * i);
;             v[4 * i] = (fkey(sv4.x) & ~127u) | (unsigned)ib; v[4 * i + 1] = (fkey(sv4.y) & ~127u) | (unsigned)(ib - 1);
;             v[4 * i + 2] = (fkey(sv4.z) & ~127u) | (unsigned)(ib - 2); v[4 * i + 3] = (fkey(sv4.w) & ~127u) | (unsigned)(ib - 3);
;         }
	v_add_u32_e32 v1, 0x7e, v1
	v_add_u32_e32 v2, 0x7d, v2
	v_bitop3_b32 v10, v11, s98, v12 bitop3:0x56
	v_and_b32_e32 v10, 0xffffff80, v10
	v_sub_u32_e32 v10, v10, v179
	v_add_u32_e32 v18, 0x7f, v10
	v_ashrrev_i32_e32 v10, 31, v13


; DI unsigned fkey(float f) { const unsigned u = __float_as_uint(f); return (u & 0x80000000u) ? ~u : (u | 0x80000000u); }
; DI void topk_phase(unsigned char* smem_, const bf16_t* __restrict__ qp, const bf16_t* __restrict__ keys, int* __restrict__ eidx, float* __restrict__ gate) {
;     ...
;         for (int i = 0; i < 8; ++i) {
;             const f32x4 sv4 = *(const f32x4*)(S + row * LDS_ + 32 * q + 4 * i);
;             const int ib = 127 - (32 * q + 4 * i);
;             v[4 * i] = (fkey(sv4.x) & ~127u) | (unsigned)ib; v[4 * i + 1] = (fkey(sv4.y) & ~127u) | (unsigned)(ib - 1);
;             v[4 * i + 2] = (fkey(sv4.z) & ~127u) | (unsigned)(ib - 2); v[4 * i + 3] = (fkey(sv4.w) & ~127u) | (unsigned)(ib - 3);
;         }
	v_add_u32_e32 v3, 0x7c, v3
	v_add_u32_e32 v4, 0x7f, v4
	v_bitop3_b32 v10, v10, s98, v13 bitop3:0x56
	v_and_b32_e32 v10, 0xffffff80, v10
	v_sub_u32_e32 v10, v10, v179
	v_add_u32_e32 v19, 0x7e, v10
	v_ashrrev_i32_e32 v10, 31, v14


; DI unsigned fkey(float f) { const unsigned u = __float_as_uint(f); return (u & 0x80000000u) ? ~u : (u | 0x80000000u); }
; DI void topk_phase(unsigned char* smem_, const bf16_t* __restrict__ qp, const bf16_t* __restrict__ keys, int* __restrict__ eidx, float* __restrict__ gate) {
;     ...
;         for (int i = 0; i < 8; ++i) {
;             const f32x4 sv4 = *(const f32x4*)(S + row * LDS_ + 32 * q + 4 * i);
;             const int ib = 127 - (32 * q + 4 * i);
;             v[4 * i] = (fkey(sv4.x) & ~127u) | (unsigned)ib; v[4 * i + 1] = (fkey(sv4.y) & ~127u) | (unsigned)(ib - 1);
;             v[4 * i + 2] = (fkey(sv4.z) & ~127u) | (unsigned)(ib - 2); v[4 * i + 3] = (fkey(sv4.w) & ~127u) | (unsigned)(ib - 3);
;         }
	v_add_u32_e32 v5, 0x7e, v5
	v_add_u32_e32 v6, 0x7d, v6
	v_bitop3_b32 v10, v10, s98, v14 bitop3:0x56
	v_and_b32_e32 v10, 0xffffff80, v10
	v_sub_u32_e32 v10, v10, v179
	v_add_u32_e32 v14, 0x7d, v10
	ds_read_b128 v[10:13], v171 offset:17472
	v_cmp_gt_i32_e32 vcc, 0, v15
	v_add_u32_e32 v7, 0x7c, v7
	v_add_u32_e32 v8, 0x7f, v8
	v_cndmask_b32_e32 v15, v21, v20, vcc
	s_waitcnt lgkmcnt(0)
	v_ashrrev_i32_e32 v20, 31, v10


; DI unsigned fkey(float f) { const unsigned u = __float_as_uint(f); return (u & 0x80000000u) ? ~u : (u | 0x80000000u); }
; DI void topk_phase(unsigned char* smem_, const bf16_t* __restrict__ qp, const bf16_t* __restrict__ keys, int* __restrict__ eidx, float* __restrict__ gate) {
;     ...
;         for (int i = 0; i < 8; ++i) {
;             const f32x4 sv4 = *(const f32x4*)(S + row * LDS_ + 32 * q + 4 * i);
;             const int ib = 127 - (32 * q + 4 * i);
;             v[4 * i] = (fkey(sv4.x) & ~127u) | (unsigned)ib; v[4 * i + 1] = (fkey(sv4.y) & ~127u) | (unsigned)(ib - 1);
;             v[4 * i + 2] = (fkey(sv4.z) & ~127u) | (unsigned)(ib - 2); v[4 * i + 3] = (fkey(sv4.w) & ~127u) | (unsigned)(ib - 3);
;         }
	v_not_b32_e32 v23, v13
	v_or_b32_e32 v24, 0x80000000, v13
	v_bitop3_b32 v10, v20, s98, v10 bitop3:0x56
	v_and_b32_e32 v10, 0xffffff80, v10
	v_sub_u32_e32 v10, v10, v180
	v_add_u32_e32 v20, 0x7f, v10
	v_not_b32_e32 v10, v11
	v_or_b32_e32 v21, 0x80000000, v11
	v_cmp_gt_i32_e32 vcc, 0, v11
	v_ashrrev_i32_e32 v11, 31, v12
	v_and_b32_e32 v15, 0xffffff80, v15
	v_cndmask_b32_e32 v10, v21, v10, vcc
	v_and_b32_e32 v10, 0xffffff80, v10
	v_sub_u32_e32 v10, v10, v180
	v_add_u32_e32 v21, 0x7e, v10


; DI unsigned fkey(float f) { const unsigned u = __float_as_uint(f); return (u & 0x80000000u) ? ~u : (u | 0x80000000u); }
; DI void topk_phase(unsigned char* smem_, const bf16_t* __restrict__ qp, const bf16_t* __restrict__ keys, int* __restrict__ eidx, float* __restrict__ gate) {
;     ...
;         for (int i = 0; i < 8; ++i) {
;             const f32x4 sv4 = *(const f32x4*)(S + row * LDS_ + 32 * q + 4 * i);
;             const int ib = 127 - (32 * q + 4 * i);
;             v[4 * i] = (fkey(sv4.x) & ~127u) | (unsigned)ib; v[4 * i + 1] = (fkey(sv4.y) & ~127u) | (unsigned)(ib - 1);
;             v[4 * i + 2] = (fkey(sv4.z) & ~127u) | (unsigned)(ib - 2); v[4 * i + 3] = (fkey(sv4.w) & ~127u) | (unsigned)(ib - 3);
;         }
	v_sub_u32_e32 v15, v15, v179
	v_add_u32_e32 v9, 0x7e, v9
	v_bitop3_b32 v10, v11, s98, v12 bitop3:0x56
	v_and_b32_e32 v10, 0xffffff80, v10
	v_sub_u32_e32 v10, v10, v180
	v_add_u32_e32 v22, 0x7d, v10
	v_cmp_gt_i32_e32 vcc, 0, v13
	ds_read_b128 v[10:13], v171 offset:17488
	v_add_u32_e32 v15, 0x7c, v15
	v_cndmask_b32_e32 v23, v24, v23, vcc
	v_and_b32_e32 v23, 0xffffff80, v23
	v_sub_u32_e32 v23, v23, v180
	s_waitcnt lgkmcnt(0)
	v_ashrrev_i32_e32 v24, 31, v10


; DI unsigned fkey(float f) { const unsigned u = __float_as_uint(f); return (u & 0x80000000u) ? ~u : (u | 0x80000000u); }
; DI void topk_phase(unsigned char* smem_, const bf16_t* __restrict__ qp, const bf16_t* __restrict__ keys, int* __restrict__ eidx, float* __restrict__ gate) {
;     ...
;         for (int i = 0; i < 8; ++i) {
;             const f32x4 sv4 = *(const f32x4*)(S + row * LDS_ + 32 * q + 4 * i);
;             const int ib = 127 - (32 * q + 4 * i);
;             v[4 * i] = (fkey(sv4.x) & ~127u) | (unsigned)ib; v[4 * i + 1] = (fkey(sv4.y) & ~127u) | (unsigned)(ib - 1);
;             v[4 * i + 2] = (fkey(sv4.z) & ~127u) | (unsigned)(ib - 2); v[4 * i + 3] = (fkey(sv4.w) & ~127u) | (unsigned)(ib - 3);
;         }
	v_not_b32_e32 v27, v13
	v_or_b32_e32 v28, 0x80000000, v13
	v_bitop3_b32 v10, v24, s98, v10 bitop3:0x56
	v_and_b32_e32 v10, 0xffffff80, v10
	v_sub_u32_e32 v10, v10, v181
	v_add_u32_e32 v24, 0x7f, v10
	v_not_b32_e32 v10, v11
	v_or_b32_e32 v25, 0x80000000, v11
	v_cmp_gt_i32_e32 vcc, 0, v11
	v_ashrrev_i32_e32 v11, 31, v12
	v_add_u32_e32 v23, 0x7c, v23
	v_cndmask_b32_e32 v10, v25, v10, vcc
	v_and_b32_e32 v10, 0xffffff80, v10
	v_sub_u32_e32 v10, v10, v181
	v_add_u32_e32 v25, 0x7e, v10


; DI unsigned fkey(float f) { const unsigned u = __float_as_uint(f); return (u & 0x80000000u) ? ~u : (u | 0x80000000u); }
; DI void topk_phase(unsigned char* smem_, const bf16_t* __restrict__ qp, const bf16_t* __restrict__ keys, int* __restrict__ eidx, float* __restrict__ gate) {
;     ...
;         for (int i = 0; i < 8; ++i) {
;             const f32x4 sv4 = *(const f32x4*)(S + row * LDS_ + 32 * q + 4 * i);
;             const int ib = 127 - (32 * q + 4 * i);
;             v[4 * i] = (fkey(sv4.x) & ~127u) | (unsigned)ib; v[4 * i + 1] = (fkey(sv4.y) & ~127u) | (unsigned)(ib - 1);
;             v[4 * i + 2] = (fkey(sv4.z) & ~127u) | (unsigned)(ib - 2); v[4 * i + 3] = (fkey(sv4.w) & ~127u) | (unsigned)(ib - 3);
;         }
	s_nop 1
	v_bitop3_b32 v10, v11, s98, v12 bitop3:0x56
	v_and_b32_e32 v10, 0xffffff80, v10
	v_sub_u32_e32 v10, v10, v181
	v_add_u32_e32 v26, 0x7d, v10
	v_cmp_gt_i32_e32 vcc, 0, v13
	ds_read_b128 v[10:13], v171 offset:17504
	s_waitcnt lgkmcnt(0)
	v_ashrrev_i32_e32 v29, 31, v10
	v_cndmask_b32_e32 v27, v28, v27, vcc


; DI unsigned fkey(float f) { const unsigned u = __float_as_uint(f); return (u & 0x80000000u) ? ~u : (u | 0x80000000u); }
; DI void topk_phase(unsigned char* smem_, const bf16_t* __restrict__ qp, const bf16_t* __restrict__ keys, int* __restrict__ eidx, float* __restrict__ gate) {
;     ...
;         for (int i = 0; i < 8; ++i) {
;             const f32x4 sv4 = *(const f32x4*)(S + row * LDS_ + 32 * q + 4 * i);
;             const int ib = 127 - (32 * q + 4 * i);
;             v[4 * i] = (fkey(sv4.x) & ~127u) | (unsigned)ib; v[4 * i + 1] = (fkey(sv4.y) & ~127u) | (unsigned)(ib - 1);
;             v[4 * i + 2] = (fkey(sv4.z) & ~127u) | (unsigned)(ib - 2); v[4 * i + 3] = (fkey(sv4.w) & ~127u) | (unsigned)(ib - 3);
;         }
	v_not_b32_e32 v31, v13
	v_or_b32_e32 v116, 0x80000000, v13
	v_bitop3_b32 v10, v29, s98, v10 bitop3:0x56
	v_and_b32_e32 v10, 0xffffff80, v10
	v_sub_u32_e32 v10, v10, v182
	v_add_u32_e32 v28, 0x7f, v10
	v_not_b32_e32 v10, v11
	v_or_b32_e32 v29, 0x80000000, v11
	v_cmp_gt_i32_e32 vcc, 0, v11
	v_ashrrev_i32_e32 v11, 31, v12
	v_and_b32_e32 v27, 0xffffff80, v27
	v_cndmask_b32_e32 v10, v29, v10, vcc
	v_and_b32_e32 v10, 0xffffff80, v10
	v_sub_u32_e32 v10, v10, v182
	v_add_u32_e32 v29, 0x7e, v10


; DI unsigned fkey(float f) { const unsigned u = __float_as_uint(f); return (u & 0x80000000u) ? ~u : (u | 0x80000000u); }
; DI void topk_phase(unsigned char* smem_, const bf16_t* __restrict__ qp, const bf16_t* __restrict__ keys, int* __restrict__ eidx, float* __restrict__ gate) {
;     ...
;         for (int i = 0; i < 8; ++i) {
;             const f32x4 sv4 = *(const f32x4*)(S + row * LDS_ + 32 * q + 4 * i);
;             const int ib = 127 - (32 * q + 4 * i);
;             v[4 * i] = (fkey(sv4.x) & ~127u) | (unsigned)ib; v[4 * i + 1] = (fkey(sv4.y) & ~127u) | (unsigned)(ib - 1);
;             v[4 * i + 2] = (fkey(sv4.z) & ~127u) | (unsigned)(ib - 2); v[4 * i + 3] = (fkey(sv4.w) & ~127u) | (unsigned)(ib - 3);
;         }
	v_sub_u32_e32 v27, v27, v181
	v_add_u32_e32 v27, 0x7c, v27
	v_bitop3_b32 v10, v11, s98, v12 bitop3:0x56
	v_and_b32_e32 v10, 0xffffff80, v10
	v_sub_u32_e32 v10, v10, v182
	v_add_u32_e32 v30, 0x7d, v10
	v_cmp_gt_i32_e32 vcc, 0, v13
	ds_read_b128 v[10:13], v171 offset:17520
	s_waitcnt lgkmcnt(0)
	v_ashrrev_i32_e32 v117, 31, v10
	v_cndmask_b32_e32 v31, v116, v31, vcc


; DI unsigned fkey(float f) { const unsigned u = __float_as_uint(f); return (u & 0x80000000u) ? ~u : (u | 0x80000000u); }
; DI void topk_phase(unsigned char* smem_, const bf16_t* __restrict__ qp, const bf16_t* __restrict__ keys, int* __restrict__ eidx, float* __restrict__ gate) {
;     ...
;         for (int i = 0; i < 8; ++i) {
;             const f32x4 sv4 = *(const f32x4*)(S + row * LDS_ + 32 * q + 4 * i);
;             const int ib = 127 - (32 * q + 4 * i);
;             v[4 * i] = (fkey(sv4.x) & ~127u) | (unsigned)ib; v[4 * i + 1] = (fkey(sv4.y) & ~127u) | (unsigned)(ib - 1);
;             v[4 * i + 2] = (fkey(sv4.z) & ~127u) | (unsigned)(ib - 2); v[4 * i + 3] = (fkey(sv4.w) & ~127u) | (unsigned)(ib - 3);
;         }
	v_and_b32_e32 v31, 0xffffff80, v31
	v_sub_u32_e32 v31, v31, v182
	v_bitop3_b32 v10, v117, s98, v10 bitop3:0x56
	v_ashrrev_i32_e32 v116, 31, v11


; DI unsigned fkey(float f) { const unsigned u = __float_as_uint(f); return (u & 0x80000000u) ? ~u : (u | 0x80000000u); }
; DI void topk_phase(unsigned char* smem_, const bf16_t* __restrict__ qp, const bf16_t* __restrict__ keys, int* __restrict__ eidx, float* __restrict__ gate) {
;     ...
;         for (int i = 0; i < 8; ++i) {
;             const f32x4 sv4 = *(const f32x4*)(S + row * LDS_ + 32 * q + 4 * i);
;             const int ib = 127 - (32 * q + 4 * i);
;             v[4 * i] = (fkey(sv4.x) & ~127u) | (unsigned)ib; v[4 * i + 1] = (fkey(sv4.y) & ~127u) | (unsigned)(ib - 1);
;             v[4 * i + 2] = (fkey(sv4.z) & ~127u) | (unsigned)(ib - 2); v[4 * i + 3] = (fkey(sv4.w) & ~127u) | (unsigned)(ib - 3);
;         }
	v_and_b32_e32 v10, 0xffffff80, v10
	v_sub_u32_e32 v10, v10, v183
	v_bitop3_b32 v11, v116, s98, v11 bitop3:0x56
	v_ashrrev_i32_e32 v116, 31, v12


; DI unsigned fkey(float f) { const unsigned u = __float_as_uint(f); return (u & 0x80000000u) ? ~u : (u | 0x80000000u); }
; DI void topk_phase(unsigned char* smem_, const bf16_t* __restrict__ qp, const bf16_t* __restrict__ keys, int* __restrict__ eidx, float* __restrict__ gate) {
;     ...
;         for (int i = 0; i < 8; ++i) {
;             const f32x4 sv4 = *(const f32x4*)(S + row * LDS_ + 32 * q + 4 * i);
;             const int ib = 127 - (32 * q + 4 * i);
;             v[4 * i] = (fkey(sv4.x) & ~127u) | (unsigned)ib; v[4 * i + 1] = (fkey(sv4.y) & ~127u) | (unsigned)(ib - 1);
;             v[4 * i + 2] = (fkey(sv4.z) & ~127u) | (unsigned)(ib - 2); v[4 * i + 3] = (fkey(sv4.w) & ~127u) | (unsigned)(ib - 3);
;         }
	v_and_b32_e32 v11, 0xffffff80, v11
	v_sub_u32_e32 v11, v11, v183
	v_bitop3_b32 v12, v116, s98, v12 bitop3:0x56
	v_ashrrev_i32_e32 v116, 31, v13


; DI unsigned fkey(float f) { const unsigned u = __float_as_uint(f); return (u & 0x80000000u) ? ~u : (u | 0x80000000u); }
; template <int N> DI void bitonic_sort_desc(unsigned (&v)[N]) {
; #pragma unroll
;     for (int k = 2; k <= N; k <<= 1)
; #pragma unroll
;         for (int j = k >> 1; j > 0; j >>= 1)
; #pragma unroll
;             for (int i = 0; i < N; ++i) { const int l = i ^ j; if (l > i) { if ((i & k) == 0) cswap(v[i], v[l]); else cswap(v[l], v[i]); } }
; }
; DI void topk_phase(unsigned char* smem_, const bf16_t* __restrict__ qp, const bf16_t* __restrict__ keys, int* __restrict__ eidx, float* __restrict__ gate) {
;     ...
;         for (int i = 0; i < 8; ++i) {
;             const f32x4 sv4 = *(const f32x4*)(S + row * LDS_ + 32 * q + 4 * i);
;             const int ib = 127 - (32 * q + 4 * i);
;             v[4 * i] = (fkey(sv4.x) & ~127u) | (unsigned)ib; v[4 * i + 1] = (fkey(sv4.y) & ~127u) | (unsigned)(ib - 1);
;             v[4 * i + 2] = (fkey(sv4.z) & ~127u) | (unsigned)(ib - 2); v[4 * i + 3] = (fkey(sv4.w) & ~127u) | (unsigned)(ib - 3);
;         }
	v_and_b32_e32 v12, 0xffffff80, v12
	v_sub_u32_e32 v12, v12, v183
	v_bitop3_b32 v13, v116, s98, v13 bitop3:0x56
	v_and_b32_e32 v13, 0xffffff80, v13
	v_sub_u32_e32 v13, v13, v183
	v_add_u32_e32 v31, 0x7c, v31
	v_add_u32_e32 v10, 0x7f, v10
	v_add_u32_e32 v11, 0x7e, v11
	v_add_u32_e32 v12, 0x7d, v12
	v_add_u32_e32 v13, 0x7c, v13
	v_max_u32_e32 v116, v0, v1
	v_min_u32_e32 v0, v0, v1
	v_max_u32_e32 v1, v3, v2
	v_min_u32_e32 v2, v3, v2
	v_max_u32_e32 v3, v4, v5
	v_min_u32_e32 v4, v4, v5
	v_max_u32_e32 v5, v7, v6
	v_min_u32_e32 v6, v7, v6
	v_max_u32_e32 v7, v8, v9
	v_min_u32_e32 v8, v8, v9
	v_max_u32_e32 v9, v17, v16
	v_min_u32_e32 v16, v17, v16
	v_max_u32_e32 v17, v18, v19
	v_min_u32_e32 v18, v18, v19
	v_max_u32_e32 v19, v15, v14
	v_min_u32_e32 v14, v15, v14
	v_max_u32_e32 v15, v20, v21
	v_min_u32_e32 v20, v20, v21
	v_max_u32_e32 v21, v23, v22
	v_min_u32_e32 v22, v23, v22
	v_max_u32_e32 v23, v24, v25
	v_min_u32_e32 v24, v24, v25
	v_max_u32_e32 v25, v27, v26
	v_min_u32_e32 v26, v27, v26
	v_max_u32_e32 v27, v28, v29
	v_min_u32_e32 v28, v28, v29
	v_max_u32_e32 v29, v31, v30
	v_min_u32_e32 v30, v31, v30
	v_max_u32_e32 v31, v10, v11
	v_min_u32_e32 v10, v10, v11
	v_max_u32_e32 v11, v13, v12
	v_min_u32_e32 v12, v13, v12
	v_max_u32_e32 v13, v116, v2
	v_min_u32_e32 v2, v116, v2
	v_max_u32_e32 v116, v0, v1
	v_min_u32_e32 v0, v0, v1
	v_max_u32_e32 v1, v6, v3
	v_min_u32_e32 v3, v6, v3
	v_max_u32_e32 v6, v5, v4
	v_min_u32_e32 v4, v5, v4
	v_max_u32_e32 v5, v7, v16
	v_min_u32_e32 v7, v7, v16
	v_max_u32_e32 v16, v8, v9
	v_min_u32_e32 v8, v8, v9
	v_max_u32_e32 v9, v14, v17
	v_min_u32_e32 v14, v14, v17
	v_max_u32_e32 v17, v19, v18
	v_min_u32_e32 v18, v19, v18
	v_max_u32_e32 v19, v15, v22
	v_min_u32_e32 v15, v15, v22
	v_max_u32_e32 v22, v20, v21
	v_min_u32_e32 v20, v20, v21
	v_max_u32_e32 v21, v26, v23
	v_min_u32_e32 v23, v26, v23
	v_max_u32_e32 v26, v25, v24
	v_min_u32_e32 v24, v25, v24
	v_max_u32_e32 v25, v27, v30
	v_min_u32_e32 v27, v27, v30
	v_max_u32_e32 v30, v28, v29
	v_min_u32_e32 v28, v28, v29
	v_max_u32_e32 v29, v12, v31
	v_min_u32_e32 v12, v12, v31
	v_max_u32_e32 v31, v11, v10
	v_min_u32_e32 v10, v11, v10
	v_max_u32_e32 v11, v13, v116
	v_min_u32_e32 v13, v13, v116
	v_max_u32_e32 v116, v2, v0
	v_min_u32_e32 v0, v2, v0
	v_max_u32_e32 v2, v4, v3
	v_min_u32_e32 v3, v4, v3
	v_max_u32_e32 v4, v6, v1
	v_min_u32_e32 v1, v6, v1
	v_max_u32_e32 v6, v5, v16
	v_min_u32_e32 v5, v5, v16
	v_max_u32_e32 v16, v7, v8
	v_min_u32_e32 v7, v7, v8
	v_max_u32_e32 v8, v18, v14
	v_min_u32_e32 v14, v18, v14
	v_max_u32_e32 v18, v17, v9
	v_min_u32_e32 v9, v17, v9
	v_max_u32_e32 v17, v19, v22
	v_min_u32_e32 v19, v19, v22
	v_max_u32_e32 v22, v15, v20
	v_min_u32_e32 v15, v15, v20
	v_max_u32_e32 v20, v24, v23
	v_min_u32_e32 v23, v24, v23
	v_max_u32_e32 v24, v26, v21
	v_min_u32_e32 v21, v26, v21
	v_max_u32_e32 v26, v25, v30
	v_min_u32_e32 v25, v25, v30
	v_max_u32_e32 v30, v27, v28
	v_min_u32_e32 v27, v27, v28
	v_max_u32_e32 v28, v10, v12
	v_min_u32_e32 v10, v10, v12
	v_max_u32_e32 v12, v31, v29
	v_min_u32_e32 v29, v31, v29
	v_max_u32_e32 v31, v11, v3
	v_min_u32_e32 v3, v11, v3
	v_max_u32_e32 v11, v13, v2
	v_min_u32_e32 v2, v13, v2
	v_max_u32_e32 v13, v116, v1
	v_min_u32_e32 v1, v116, v1
	v_max_u32_e32 v116, v0, v4
	v_min_u32_e32 v0, v0, v4
	v_max_u32_e32 v4, v14, v6
	v_min_u32_e32 v6, v14, v6
	v_max_u32_e32 v14, v8, v5
	v_min_u32_e32 v5, v8, v5
	v_max_u32_e32 v8, v9, v16
	v_min_u32_e32 v9, v9, v16
	v_max_u32_e32 v16, v18, v7
	v_min_u32_e32 v7, v18, v7
	v_max_u32_e32 v18, v17, v23
	v_min_u32_e32 v17, v17, v23
	v_max_u32_e32 v23, v19, v20
	v_min_u32_e32 v19, v19, v20
	v_max_u32_e32 v20, v22, v21
	v_min_u32_e32 v21, v22, v21
	v_max_u32_e32 v22, v15, v24
	v_min_u32_e32 v15, v15, v24
	v_max_u32_e32 v24, v10, v26
	v_min_u32_e32 v10, v10, v26
	v_max_u32_e32 v26, v28, v25
	v_min_u32_e32 v25, v28, v25
	v_max_u32_e32 v28, v29, v30
	v_min_u32_e32 v29, v29, v30
	v_max_u32_e32 v30, v12, v27
	v_min_u32_e32 v12, v12, v27
	v_max_u32_e32 v27, v31, v13
	v_min_u32_e32 v13, v31, v13
	v_max_u32_e32 v31, v11, v116
	v_min_u32_e32 v11, v11, v116
	v_max_u32_e32 v116, v3, v1
	v_min_u32_e32 v1, v3, v1
	v_max_u32_e32 v3, v2, v0
	v_min_u32_e32 v0, v2, v0
	v_max_u32_e32 v2, v9, v6
	v_min_u32_e32 v6, v9, v6
	v_max_u32_e32 v9, v7, v5
	v_min_u32_e32 v5, v7, v5
	v_max_u32_e32 v7, v8, v4
	v_min_u32_e32 v4, v8, v4
	v_max_u32_e32 v8, v16, v14
	v_min_u32_e32 v14, v16, v14
	v_max_u32_e32 v16, v18, v20
	v_min_u32_e32 v18, v18, v20
	v_max_u32_e32 v20, v23, v22
	v_min_u32_e32 v22, v23, v22
	v_max_u32_e32 v23, v17, v21
	v_min_u32_e32 v17, v17, v21
	v_max_u32_e32 v21, v19, v15
	v_min_u32_e32 v15, v19, v15
	v_max_u32_e32 v19, v29, v10
	v_min_u32_e32 v10, v29, v10
	v_max_u32_e32 v29, v12, v25
	v_min_u32_e32 v12, v12, v25
	v_max_u32_e32 v25, v28, v24
	v_min_u32_e32 v24, v28, v24
	v_max_u32_e32 v28, v30, v26
	v_min_u32_e32 v26, v30, v26
	v_max_u32_e32 v30, v27, v31
	v_min_u32_e32 v27, v27, v31
	v_max_u32_e32 v31, v13, v11
	v_min_u32_e32 v11, v13, v11
	v_max_u32_e32 v13, v116, v3
	v_min_u32_e32 v3, v116, v3
	v_max_u32_e32 v116, v1, v0
	v_min_u32_e32 v0, v1, v0
	v_max_u32_e32 v1, v5, v6
	v_min_u32_e32 v5, v5, v6
	v_max_u32_e32 v6, v9, v2
	v_min_u32_e32 v2, v9, v2
	v_max_u32_e32 v9, v14, v4
	v_min_u32_e32 v4, v14, v4
	v_max_u32_e32 v14, v8, v7
	v_min_u32_e32 v7, v8, v7
	v_max_u32_e32 v8, v16, v20
	v_min_u32_e32 v16, v16, v20
	v_max_u32_e32 v20, v18, v22
	v_min_u32_e32 v18, v18, v22
	v_max_u32_e32 v22, v23, v21
	v_min_u32_e32 v21, v23, v21
	v_max_u32_e32 v23, v17, v15
	v_min_u32_e32 v15, v17, v15
	v_max_u32_e32 v17, v12, v10
	v_min_u32_e32 v10, v12, v10
	v_max_u32_e32 v12, v29, v19
	v_min_u32_e32 v19, v29, v19
	v_max_u32_e32 v29, v26, v24
; template <int N> DI void bitonic_sort_desc(unsigned (&v)[N]) {
; #pragma unroll
;     for (int k = 2; k <= N; k <<= 1)
; #pragma unroll
;         for (int j = k >> 1; j > 0; j >>= 1)
; #pragma unroll
;             for (int i = 0; i < N; ++i) { const int l = i ^ j; if (l > i) { if ((i & k) == 0) cswap(v[i], v[l]); else cswap(v[l], v[i]); } }
; }
; DI void merge_top16(unsigned (&v)[16], int st) {
;     unsigned x[16];
; #pragma unroll
;     for (int i = 0; i < 16; ++i) x[i] = (unsigned)__shfl_xor((int)v[15 - i], st);
; #pragma unroll
;     for (int i = 0; i < 16; ++i) v[i] = max(v[i], x[i]);
; #pragma unroll
;     for (int j = 8; j > 0; j >>= 1)
; #pragma unroll
;         for (int i = 0; i < 16; ++i) { const int l = i ^ j; if (l > i) cswap(v[i], v[l]); }
; }
; DI void topk_phase(unsigned char* smem_, const bf16_t* __restrict__ qp, const bf16_t* __restrict__ keys, int* __restrict__ eidx, float* __restrict__ gate) {
;     ...
;         bitonic_sort_desc<32>(v);
;         unsigned t16[16];
; #pragma unroll
;         for (int i = 0; i < 16; ++i) t16[i] = v[i];
;         merge_top16(t16, 1);
	v_min_u32_e32 v24, v26, v24
	v_max_u32_e32 v26, v28, v25
	v_min_u32_e32 v25, v28, v25
	v_max_u32_e32 v28, v30, v5
	v_min_u32_e32 v5, v30, v5
	v_max_u32_e32 v30, v27, v1
	v_min_u32_e32 v1, v27, v1
	v_max_u32_e32 v27, v31, v2
	v_min_u32_e32 v2, v31, v2
	v_max_u32_e32 v31, v11, v6
	v_min_u32_e32 v6, v11, v6
	v_max_u32_e32 v11, v13, v4
	v_min_u32_e32 v4, v13, v4
	v_max_u32_e32 v13, v3, v9
	v_min_u32_e32 v3, v3, v9
	v_max_u32_e32 v9, v116, v7
	v_min_u32_e32 v7, v116, v7
	v_max_u32_e32 v116, v0, v14
	v_min_u32_e32 v0, v0, v14
	v_max_u32_e32 v14, v10, v8
	v_min_u32_e32 v8, v10, v8
	v_max_u32_e32 v10, v17, v16
	v_min_u32_e32 v16, v17, v16
	v_max_u32_e32 v17, v19, v20
	v_min_u32_e32 v19, v19, v20
	v_max_u32_e32 v20, v12, v18
	v_min_u32_e32 v12, v12, v18
	v_max_u32_e32 v18, v24, v22
	v_min_u32_e32 v22, v24, v22
	v_max_u32_e32 v24, v29, v21
	v_min_u32_e32 v21, v29, v21
	v_max_u32_e32 v29, v25, v23
	v_min_u32_e32 v23, v25, v23
	v_max_u32_e32 v25, v26, v15
	v_min_u32_e32 v15, v26, v15
	v_max_u32_e32 v26, v28, v11
	v_min_u32_e32 v11, v28, v11
	v_max_u32_e32 v28, v30, v13
	v_min_u32_e32 v13, v30, v13
	v_max_u32_e32 v30, v27, v9
	v_min_u32_e32 v9, v27, v9
	v_max_u32_e32 v27, v31, v116
	v_min_u32_e32 v31, v31, v116
	v_max_u32_e32 v116, v5, v4
	v_min_u32_e32 v4, v5, v4
	v_max_u32_e32 v5, v1, v3
	v_min_u32_e32 v1, v1, v3
	v_max_u32_e32 v3, v2, v7
	v_min_u32_e32 v2, v2, v7
	v_max_u32_e32 v7, v6, v0
	v_min_u32_e32 v0, v6, v0
	v_max_u32_e32 v6, v22, v8
	v_min_u32_e32 v8, v22, v8
	v_max_u32_e32 v22, v21, v16
	v_min_u32_e32 v16, v21, v16
	v_max_u32_e32 v21, v23, v19
	v_min_u32_e32 v19, v23, v19
	v_max_u32_e32 v23, v15, v12
	v_min_u32_e32 v12, v15, v12
	v_max_u32_e32 v15, v18, v14
	v_min_u32_e32 v14, v18, v14
	v_max_u32_e32 v18, v24, v10
	v_min_u32_e32 v10, v24, v10
	v_max_u32_e32 v24, v29, v17
	v_min_u32_e32 v17, v29, v17
	v_max_u32_e32 v29, v25, v20
	v_min_u32_e32 v20, v25, v20
	v_max_u32_e32 v25, v26, v30
	v_min_u32_e32 v26, v26, v30
	v_max_u32_e32 v30, v28, v27
	v_min_u32_e32 v27, v28, v27
	v_max_u32_e32 v28, v11, v9
	v_min_u32_e32 v9, v11, v9
	v_max_u32_e32 v11, v13, v31
	v_min_u32_e32 v13, v13, v31
	v_max_u32_e32 v31, v116, v3
	v_min_u32_e32 v3, v116, v3
	v_max_u32_e32 v116, v5, v7
	v_min_u32_e32 v5, v5, v7
	v_max_u32_e32 v7, v4, v2
	v_min_u32_e32 v2, v4, v2
	v_max_u32_e32 v4, v1, v0
	v_min_u32_e32 v0, v1, v0
	v_max_u32_e32 v1, v19, v8
	v_min_u32_e32 v8, v19, v8
	v_max_u32_e32 v19, v12, v16
	v_min_u32_e32 v12, v12, v16
	v_max_u32_e32 v16, v21, v6
	v_min_u32_e32 v6, v21, v6
	v_max_u32_e32 v21, v23, v22
	v_min_u32_e32 v22, v23, v22
	v_max_u32_e32 v23, v17, v14
	v_min_u32_e32 v14, v17, v14
	v_max_u32_e32 v17, v20, v10
	v_min_u32_e32 v10, v20, v10
	v_max_u32_e32 v20, v24, v15
	v_min_u32_e32 v15, v24, v15
	v_max_u32_e32 v24, v29, v18
	v_min_u32_e32 v18, v29, v18
	v_min_u32_e32 v29, v25, v30
	v_min_u32_e32 v117, v26, v27
	v_min_u32_e32 v118, v28, v11
	v_min_u32_e32 v119, v9, v13
	v_min_u32_e32 v120, v31, v116
	v_min_u32_e32 v121, v3, v5
	v_min_u32_e32 v122, v7, v4
	v_min_u32_e32 v123, v2, v0
	v_min_u32_e32 v124, v12, v8
	v_min_u32_e32 v125, v19, v1
	v_min_u32_e32 v126, v22, v6
	v_min_u32_e32 v127, v21, v16
	v_min_u32_e32 v142, v10, v14
	v_min_u32_e32 v143, v17, v23
	v_min_u32_e32 v144, v18, v15
	v_min_u32_e32 v145, v24, v20
	v_max3_u32 v25, v25, v30, v124
	v_max3_u32 v8, v29, v12, v8
	v_max3_u32 v12, v26, v27, v125
	v_max3_u32 v1, v117, v19, v1
	v_max3_u32 v11, v28, v11, v126
	v_max3_u32 v6, v118, v22, v6
	v_max3_u32 v9, v9, v13, v127
	v_max3_u32 v13, v119, v21, v16
	v_max3_u32 v16, v31, v116, v142
	v_max3_u32 v10, v120, v10, v14
	v_max3_u32 v3, v3, v5, v143
	v_max3_u32 v5, v121, v17, v23
	v_max3_u32 v4, v7, v4, v144
	v_max3_u32 v7, v122, v18, v15
	v_max3_u32 v0, v2, v0, v145
	v_max3_u32 v2, v123, v24, v20
	v_max_u32_e32 v14, v25, v16
	v_min_u32_e32 v15, v25, v16
	v_max_u32_e32 v16, v8, v10
	v_min_u32_e32 v8, v8, v10
	v_max_u32_e32 v10, v12, v3
	v_min_u32_e32 v3, v12, v3
	v_max_u32_e32 v12, v1, v5
	v_min_u32_e32 v1, v1, v5
	v_max_u32_e32 v5, v11, v4
	v_min_u32_e32 v4, v11, v4
	v_max_u32_e32 v11, v6, v7
	v_min_u32_e32 v6, v6, v7
	v_max_u32_e32 v7, v9, v0
	v_min_u32_e32 v0, v9, v0
	v_max_u32_e32 v9, v13, v2
	v_min_u32_e32 v2, v13, v2
	v_max_u32_e32 v13, v14, v5
	v_min_u32_e32 v5, v14, v5
	v_max_u32_e32 v14, v16, v11
	v_min_u32_e32 v11, v16, v11
	v_max_u32_e32 v16, v10, v7
	v_min_u32_e32 v7, v10, v7
	v_max_u32_e32 v10, v12, v9
	v_min_u32_e32 v9, v12, v9
	v_max_u32_e32 v12, v15, v4
	v_min_u32_e32 v4, v15, v4
	v_max_u32_e32 v15, v8, v6
	v_min_u32_e32 v6, v8, v6
	v_max_u32_e32 v8, v3, v0
	v_min_u32_e32 v0, v3, v0
	v_max_u32_e32 v3, v1, v2
	v_min_u32_e32 v1, v1, v2
	v_max_u32_e32 v2, v13, v16
	v_min_u32_e32 v13, v13, v16
	v_max_u32_e32 v16, v14, v10
	v_min_u32_e32 v10, v14, v10
	v_max_u32_e32 v14, v5, v7
	v_min_u32_e32 v5, v5, v7
	v_max_u32_e32 v7, v11, v9
	v_min_u32_e32 v9, v11, v9
	v_max_u32_e32 v11, v12, v8
	v_min_u32_e32 v8, v12, v8
	v_max_u32_e32 v12, v15, v3
	v_min_u32_e32 v3, v15, v3
	v_max_u32_e32 v15, v4, v0
	v_min_u32_e32 v0, v4, v0
	v_max_u32_e32 v4, v6, v1
	v_min_u32_e32 v1, v6, v1
	v_max_u32_e32 v6, v2, v16
	v_min_u32_e32 v2, v2, v16
	v_max_u32_e32 v16, v13, v10
	v_min_u32_e32 v10, v13, v10
	v_max_u32_e32 v13, v14, v7
	v_min_u32_e32 v7, v14, v7
	v_max_u32_e32 v14, v5, v9
	v_min_u32_e32 v5, v5, v9
	v_max_u32_e32 v9, v11, v12
	v_min_u32_e32 v11, v11, v12
	v_max_u32_e32 v12, v8, v3
	v_min_u32_e32 v3, v8, v3
	v_max_u32_e32 v8, v15, v4
	v_min_u32_e32 v4, v15, v4
	v_max_u32_e32 v15, v0, v1
	v_min_u32_e32 v0, v0, v1
	s_nop 1
	v_mov_b32_dpp v1, v0 quad_perm:[1,0,3,2] row_mask:0xf bank_mask:0xf
	v_mov_b32_dpp v17, v15 quad_perm:[1,0,3,2] row_mask:0xf bank_mask:0xf
	v_mov_b32_dpp v18, v4 quad_perm:[1,0,3,2] row_mask:0xf bank_mask:0xf
	v_mov_b32_dpp v19, v8 quad_perm:[1,0,3,2] row_mask:0xf bank_mask:0xf
	v_mov_b32_dpp v20, v3 quad_perm:[1,0,3,2] row_mask:0xf bank_mask:0xf
	v_mov_b32_dpp v21, v12 quad_perm:[1,0,3,2] row_mask:0xf bank_mask:0xf
	v_mov_b32_dpp v22, v11 quad_perm:[1,0,3,2] row_mask:0xf bank_mask:0xf
	v_mov_b32_dpp v23, v9 quad_perm:[1,0,3,2] row_mask:0xf bank_mask:0xf
	v_mov_b32_dpp v24, v5 quad_perm:[1,0,3,2] row_mask:0xf bank_mask:0xf
	v_mov_b32_dpp v25, v14 quad_perm:[1,0,3,2] row_mask:0xf bank_mask:0xf
	v_mov_b32_dpp v26, v7 quad_perm:[1,0,3,2] row_mask:0xf bank_mask:0xf
	v_mov_b32_dpp v27, v13 quad_perm:[1,0,3,2] row_mask:0xf bank_mask:0xf
	v_mov_b32_dpp v28, v10 quad_perm:[1,0,3,2] row_mask:0xf bank_mask:0xf
	v_mov_b32_dpp v29, v16 quad_perm:[1,0,3,2] row_mask:0xf bank_mask:0xf
	v_mov_b32_dpp v30, v2 quad_perm:[1,0,3,2] row_mask:0xf bank_mask:0xf
	v_mov_b32_dpp v31, v6 quad_perm:[1,0,3,2] row_mask:0xf bank_mask:0xf
	s_waitcnt lgkmcnt(0)
; DI void merge_top16(unsigned (&v)[16], int st) {
;     unsigned x[16];
; #pragma unroll
;     for (int i = 0; i < 16; ++i) x[i] = (unsigned)__shfl_xor((int)v[15 - i], st);
; #pragma unroll
;     for (int i = 0; i < 16; ++i) v[i] = max(v[i], x[i]);
; #pragma unroll
;     for (int j = 8; j > 0; j >>= 1)
; #pragma unroll
;         for (int i = 0; i < 16; ++i) { const int l = i ^ j; if (l > i) cswap(v[i], v[l]); }
; }
; DI void topk_phase(unsigned char* smem_, const bf16_t* __restrict__ qp, const bf16_t* __restrict__ keys, int* __restrict__ eidx, float* __restrict__ gate) {
;     ...
;         merge_top16(t16, 2);
; #pragma unroll
;         for (int i = 0; i < 16; ++i) if ((i >> 2) == q) { const int idx = 127 - (int)(t16[i] & 127u); SI[row * 32 + 16 * p + i] = idx; SV[row * 32 + 16 * p + i] = S[row * LDS_ + idx]; }
	v_max_u32_e32 v1, v6, v1
	v_max_u32_e32 v2, v2, v17
	v_max_u32_e32 v6, v16, v18
	v_max_u32_e32 v10, v10, v19
	v_max_u32_e32 v13, v13, v20
	v_max_u32_e32 v7, v7, v21
	v_max_u32_e32 v14, v14, v22
	v_max_u32_e32 v5, v5, v23
	v_max_u32_e32 v9, v9, v24
	v_max_u32_e32 v11, v11, v25
	v_max_u32_e32 v12, v12, v26
	v_max_u32_e32 v3, v3, v27
	v_max_u32_e32 v8, v8, v28
	v_max_u32_e32 v4, v4, v29
	v_max_u32_e32 v15, v15, v30
	v_max_u32_e32 v0, v0, v31
	v_max_u32_e32 v16, v1, v9
	v_min_u32_e32 v1, v1, v9
	v_max_u32_e32 v9, v2, v11
	v_min_u32_e32 v2, v2, v11
	v_max_u32_e32 v11, v6, v12
	v_min_u32_e32 v6, v6, v12
	v_max_u32_e32 v12, v10, v3
	v_min_u32_e32 v3, v10, v3
	v_max_u32_e32 v10, v13, v8
	v_min_u32_e32 v8, v13, v8
	v_max_u32_e32 v13, v7, v4
	v_min_u32_e32 v4, v7, v4
	v_max_u32_e32 v7, v14, v15
	v_min_u32_e32 v14, v14, v15
	v_max_u32_e32 v15, v5, v0
	v_min_u32_e32 v0, v5, v0
	v_max_u32_e32 v5, v16, v10
	v_min_u32_e32 v10, v16, v10
	v_max_u32_e32 v16, v9, v13
	v_min_u32_e32 v9, v9, v13
	v_max_u32_e32 v13, v11, v7
	v_min_u32_e32 v7, v11, v7
	v_max_u32_e32 v11, v12, v15
	v_min_u32_e32 v12, v12, v15
	v_max_u32_e32 v15, v1, v8
	v_min_u32_e32 v1, v1, v8
	v_max_u32_e32 v8, v2, v4
	v_min_u32_e32 v2, v2, v4
	v_max_u32_e32 v4, v6, v14
	v_min_u32_e32 v6, v6, v14
	v_max_u32_e32 v14, v3, v0
	v_min_u32_e32 v0, v3, v0
	v_max_u32_e32 v3, v5, v13
	v_min_u32_e32 v5, v5, v13
	v_max_u32_e32 v13, v16, v11
	v_min_u32_e32 v11, v16, v11
	v_max_u32_e32 v16, v10, v7
	v_min_u32_e32 v7, v10, v7
	v_max_u32_e32 v10, v9, v12
	v_min_u32_e32 v9, v9, v12
	v_max_u32_e32 v12, v15, v4
	v_min_u32_e32 v4, v15, v4
	v_max_u32_e32 v15, v8, v14
	v_min_u32_e32 v8, v8, v14
	v_max_u32_e32 v14, v1, v6
	v_min_u32_e32 v1, v1, v6
	v_max_u32_e32 v6, v2, v0
	v_min_u32_e32 v0, v2, v0
	v_max_u32_e32 v2, v3, v13
	v_min_u32_e32 v3, v3, v13
	v_max_u32_e32 v13, v5, v11
	v_min_u32_e32 v5, v5, v11
	v_max_u32_e32 v11, v16, v10
	v_min_u32_e32 v10, v16, v10
	v_max_u32_e32 v16, v7, v9
	v_min_u32_e32 v7, v7, v9
	v_max_u32_e32 v9, v12, v15
	v_min_u32_e32 v12, v12, v15
	v_max_u32_e32 v15, v4, v8
	v_min_u32_e32 v17, v4, v8
	v_max_u32_e32 v18, v14, v6
	v_min_u32_e32 v14, v14, v6
	v_max_u32_e32 v19, v1, v0
	v_min_u32_e32 v20, v1, v0
	s_nop 1
	v_mov_b32_dpp v0, v20 quad_perm:[2,3,0,1] row_mask:0xf bank_mask:0xf
	v_mov_b32_dpp v1, v19 quad_perm:[2,3,0,1] row_mask:0xf bank_mask:0xf
	v_mov_b32_dpp v4, v14 quad_perm:[2,3,0,1] row_mask:0xf bank_mask:0xf
	v_mov_b32_dpp v6, v18 quad_perm:[2,3,0,1] row_mask:0xf bank_mask:0xf
	v_mov_b32_dpp v8, v17 quad_perm:[2,3,0,1] row_mask:0xf bank_mask:0xf
	v_mov_b32_dpp v21, v15 quad_perm:[2,3,0,1] row_mask:0xf bank_mask:0xf
	v_mov_b32_dpp v22, v12 quad_perm:[2,3,0,1] row_mask:0xf bank_mask:0xf
	v_mov_b32_dpp v23, v9 quad_perm:[2,3,0,1] row_mask:0xf bank_mask:0xf
	v_mov_b32_dpp v24, v7 quad_perm:[2,3,0,1] row_mask:0xf bank_mask:0xf
	v_mov_b32_dpp v25, v16 quad_perm:[2,3,0,1] row_mask:0xf bank_mask:0xf
	v_mov_b32_dpp v26, v10 quad_perm:[2,3,0,1] row_mask:0xf bank_mask:0xf
	v_mov_b32_dpp v27, v11 quad_perm:[2,3,0,1] row_mask:0xf bank_mask:0xf
	v_mov_b32_dpp v28, v5 quad_perm:[2,3,0,1] row_mask:0xf bank_mask:0xf
	v_mov_b32_dpp v29, v13 quad_perm:[2,3,0,1] row_mask:0xf bank_mask:0xf
	v_mov_b32_dpp v30, v3 quad_perm:[2,3,0,1] row_mask:0xf bank_mask:0xf
	v_mov_b32_dpp v31, v2 quad_perm:[2,3,0,1] row_mask:0xf bank_mask:0xf
	s_waitcnt lgkmcnt(0)
	v_max_u32_e32 v0, v2, v0
	v_max_u32_e32 v1, v3, v1
	v_max_u32_e32 v2, v13, v4
	v_max_u32_e32 v3, v5, v6
	v_max_u32_e32 v4, v11, v8
	v_max_u32_e32 v5, v10, v21
	v_max_u32_e32 v6, v16, v22
	v_max_u32_e32 v7, v7, v23
	v_max_u32_e32 v8, v9, v24
	v_max_u32_e32 v9, v12, v25
	v_max_u32_e32 v10, v15, v26
	v_max_u32_e32 v11, v17, v27
	v_max_u32_e32 v12, v18, v28
	v_max_u32_e32 v13, v14, v29
	v_max_u32_e32 v14, v19, v30
	v_max_u32_e32 v15, v20, v31
	v_max_u32_e32 v16, v0, v8
	v_max_u32_e32 v17, v1, v9
	v_max_u32_e32 v18, v2, v10
	v_max_u32_e32 v19, v3, v11
	v_max_u32_e32 v20, v4, v12
	v_max_u32_e32 v21, v5, v13
	v_max_u32_e32 v22, v6, v14
	v_max_u32_e32 v23, v7, v15
	s_or_b64 s[0:1], s[4:5], s[6:7]
	s_or_b64 vcc, s[6:7], s[10:11]
	v_min_u32_e32 v0, v0, v8
	v_min_u32_e32 v1, v1, v9
	v_min_u32_e32 v2, v2, v10
	v_min_u32_e32 v3, v3, v11
	v_min_u32_e32 v4, v4, v12
	v_min_u32_e32 v5, v5, v13
	v_min_u32_e32 v6, v6, v14
	v_min_u32_e32 v7, v7, v15
	v_add_u32_e32 v116, 0xf000, v184
	v_cndmask_b32_e64 v0, v0, v16, s[0:1]
	v_cndmask_b32_e64 v1, v1, v17, s[0:1]
	v_cndmask_b32_e64 v2, v2, v18, s[0:1]
	v_cndmask_b32_e64 v3, v3, v19, s[0:1]
	v_cndmask_b32_e64 v4, v4, v20, s[0:1]
	v_cndmask_b32_e64 v5, v5, v21, s[0:1]
	v_cndmask_b32_e64 v6, v6, v22, s[0:1]
	v_cndmask_b32_e64 v7, v7, v23, s[0:1]
	v_max_u32_e32 v8, v0, v4
	v_max_u32_e32 v9, v1, v5
	v_max_u32_e32 v10, v2, v6
	v_max_u32_e32 v11, v3, v7
	v_min_u32_e32 v12, v0, v4
	v_min_u32_e32 v13, v1, v5
	v_min_u32_e32 v14, v2, v6
	v_min_u32_e32 v15, v3, v7
	v_cndmask_b32_e32 v0, v8, v12, vcc
	v_cndmask_b32_e32 v1, v9, v13, vcc
	v_cndmask_b32_e32 v2, v10, v14, vcc
	v_cndmask_b32_e32 v3, v11, v15, vcc
	v_max_u32_e32 v4, v0, v2
	v_min_u32_e32 v5, v0, v2
	v_max_u32_e32 v6, v1, v3
	v_min_u32_e32 v7, v1, v3
	v_max_u32_e32 v0, v4, v6
	v_min_u32_e32 v1, v4, v6
	v_max_u32_e32 v2, v5, v7
	v_min_u32_e32 v3, v5, v7
	v_xor_b32_e32 v0, -1, v0
	v_xor_b32_e32 v1, -1, v1
	v_xor_b32_e32 v2, -1, v2
	v_xor_b32_e32 v3, -1, v3
	v_and_b32_e32 v0, 0x7f, v0
	v_and_b32_e32 v1, 0x7f, v1
	v_and_b32_e32 v2, 0x7f, v2
	v_and_b32_e32 v3, 0x7f, v3
	v_lshl_add_u32 v4, v0, 2, v169
	v_lshl_add_u32 v5, v1, 2, v169
	v_lshl_add_u32 v6, v2, 2, v169
	v_lshl_add_u32 v7, v3, 2, v169
	ds_read_b32 v4, v4 offset:17408
	ds_read_b32 v5, v5 offset:17408
	ds_read_b32 v6, v6 offset:17408
	ds_read_b32 v7, v7 offset:17408
	ds_write_b128 v253, v[0:3] offset:61440
	s_waitcnt lgkmcnt(1)
	ds_write_b128 v253, v[4:7] offset:53248
	s_waitcnt vmcnt(3)
	ds_write_b128 v234, v[96:99]
	s_waitcnt vmcnt(2)
	ds_write_b128 v234, v[100:103] offset:4352
	s_waitcnt vmcnt(1)
	ds_write_b128 v234, v[104:107] offset:8704
	s_waitcnt vmcnt(0)
	ds_write_b128 v234, v[108:111] offset:13056
	s_waitcnt lgkmcnt(0)
	s_barrier
; #define MFMA32(a, b, c) __builtin_amdgcn_mfma_f32_32x32x16_bf16((a), (b), (c), 0, 0, 0)
; #define TK_PREFETCH(t_, p_) do { const int tk0_ = ((t_) >> 3) * 64, hp_ = ((t_) & 7) * 2 + (p_); \
;         _Pragma("unroll") for (int i_ = 0; i_ < 4; ++i_) { const int c_ = tid + 256 * i_; pre[i_] = *(const u32x4*)(qp + (size_t)(tk0_ + (c_ >> 4)) * 2048 + hp_ * 128 + (c_ & 15) * 8); } } while (0)
; DI void topk_phase(unsigned char* smem_, const bf16_t* __restrict__ qp, const bf16_t* __restrict__ keys, int* __restrict__ eidx, float* __restrict__ gate) {
;     ...
;     for (int p = 0; p < 2; ++p) {
; #pragma unroll
;         for (int i = 0; i < 4; ++i) { const int c = tid + 256 * i; *(u32x4*)(As + (c >> 4) * LDA + (c & 15) * 8) = pre[i]; }
;         __syncthreads();
;         f32x16 acc[2];
; #pragma unroll
;         for (int i = 0; i < 16; ++i) { acc[0][i] = 0.f; acc[1][i] = 0.f; }
; #pragma unroll
;         for (int ks = 0; ks < 8; ++ks) {
; #pragma unroll
;             for (int th = 0; th < 2; ++th) { const bf16x8 qf = *(const bf16x8*)(As + (32 * th + l31) * LDA + ks * 16 + hi * 8); acc[th] = MFMA32(kf[p][ks], qf, acc[th]); }
;         }
; #pragma unroll
;         for (int th = 0; th < 2; ++th)
; #pragma unroll
;             for (int g = 0; g < 4; ++g) { f32x4 o; o.x = acc[th][4 * g]; o.y = acc[th][4 * g + 1]; o.z = acc[th][4 * g + 2]; o.w = acc[th][4 * g + 3]; *(f32x4*)(S + (32 * th + l31) * LDS_ + 32 * wid + 8 * g + 4 * hi) = o; }
;         __syncthreads();
;         if (p == 0) TK_PREFETCH(t, 1); else if (t + G < NT) TK_PREFETCH(t + G, 0);
	ds_read_b128 v[0:3], v235
	ds_read_b128 v[118:121], v235 offset:32
	s_waitcnt lgkmcnt(1)
	v_mfma_f32_32x32x16_bf16 v[16:31], v[64:67], v[0:3], 0
	ds_read_b128 v[0:3], v235 offset:8704
	s_add_i32 s18, s18, s82
	s_cmpk_gt_i32 s18, 0xfff
	s_cselect_b64 s[0:1], -1, 0
	v_readlane_b32 s16, v251, 51
	s_add_i32 s22, s16, s22
	s_and_b64 vcc, exec, s[0:1]
	s_waitcnt lgkmcnt(1)
	v_mfma_f32_32x32x16_bf16 v[16:31], v[68:71], v[118:121], v[16:31]
	ds_read_b128 v[118:121], v235 offset:8736
	s_waitcnt lgkmcnt(1)
	v_mfma_f32_32x32x16_bf16 v[0:15], v[64:67], v[0:3], 0
	s_waitcnt lgkmcnt(0)
	v_mfma_f32_32x32x16_bf16 v[0:15], v[68:71], v[118:121], v[0:15]
	ds_read_b128 v[118:121], v235 offset:64
	s_waitcnt lgkmcnt(0)
	v_mfma_f32_32x32x16_bf16 v[16:31], v[72:75], v[118:121], v[16:31]
	ds_read_b128 v[118:121], v235 offset:8768
	s_waitcnt lgkmcnt(0)
	v_mfma_f32_32x32x16_bf16 v[0:15], v[72:75], v[118:121], v[0:15]
	ds_read_b128 v[118:121], v235 offset:96
	s_waitcnt lgkmcnt(0)
	v_mfma_f32_32x32x16_bf16 v[16:31], v[76:79], v[118:121], v[16:31]
	ds_read_b128 v[118:121], v235 offset:8800
	s_waitcnt lgkmcnt(0)
	v_mfma_f32_32x32x16_bf16 v[0:15], v[76:79], v[118:121], v[0:15]
	ds_read_b128 v[118:121], v235 offset:128
	s_waitcnt lgkmcnt(0)
	v_mfma_f32_32x32x16_bf16 v[16:31], v[80:83], v[118:121], v[16:31]
	ds_read_b128 v[118:121], v235 offset:8832
	s_waitcnt lgkmcnt(0)
	v_mfma_f32_32x32x16_bf16 v[0:15], v[80:83], v[118:121], v[0:15]
	ds_read_b128 v[118:121], v235 offset:160
	s_waitcnt lgkmcnt(0)
	v_mfma_f32_32x32x16_bf16 v[16:31], v[84:87], v[118:121], v[16:31]
	ds_read_b128 v[118:121], v235 offset:8864
	s_waitcnt lgkmcnt(0)
	v_mfma_f32_32x32x16_bf16 v[0:15], v[84:87], v[118:121], v[0:15]
	ds_read_b128 v[118:121], v235 offset:192
	s_waitcnt lgkmcnt(0)
	v_mfma_f32_32x32x16_bf16 v[16:31], v[88:91], v[118:121], v[16:31]
	ds_read_b128 v[118:121], v235 offset:8896
	s_waitcnt lgkmcnt(0)
	v_mfma_f32_32x32x16_bf16 v[0:15], v[88:91], v[118:121], v[0:15]
	ds_read_b128 v[118:121], v235 offset:224
	s_waitcnt lgkmcnt(0)
	v_mfma_f32_32x32x16_bf16 v[16:31], v[92:95], v[118:121], v[16:31]
	ds_read_b128 v[118:121], v235 offset:8928
	s_nop 10
	ds_write_b128 v236, v[16:19] offset:17408
	ds_write_b128 v236, v[20:23] offset:17440
	ds_write_b128 v236, v[24:27] offset:17472
	ds_write_b128 v236, v[28:31] offset:17504
	s_waitcnt lgkmcnt(4)
	v_mfma_f32_32x32x16_bf16 v[0:15], v[92:95], v[118:121], v[0:15]
	s_nop 11
	ds_write_b128 v236, v[0:3] offset:34304
	ds_write_b128 v236, v[4:7] offset:34336
	ds_write_b128 v236, v[8:11] offset:34368
	ds_write_b128 v236, v[12:15] offset:34400
	s_waitcnt lgkmcnt(0)
	s_barrier
	s_cbranch_vccnz .LBB0_67
	s_and_b32 s16, s22, 0xffffffc0
	s_and_b32 s17, s21, 0x700
	v_or_b32_e32 v2, s16, v165
	s_lshl_b32 s60, s17, 1
	v_ashrrev_i32_e32 v3, 31, v2
	v_or_b32_e32 v4, s16, v166
	v_lshl_add_u64 v[0:1], v[114:115], 0, s[60:61]
	v_lshlrev_b64 v[2:3], 12, v[2:3]
	v_ashrrev_i32_e32 v5, 31, v4
	v_lshl_add_u64 v[2:3], v[0:1], 0, v[2:3]
	v_lshlrev_b64 v[4:5], 12, v[4:5]
	v_lshl_add_u64 v[4:5], v[0:1], 0, v[4:5]
	global_load_dwordx4 v[96:99], v[2:3], off
	global_load_dwordx4 v[100:103], v[4:5], off
	v_or_b32_e32 v2, s16, v167
	v_ashrrev_i32_e32 v3, 31, v2
	v_or_b32_e32 v4, s16, v168
	v_lshlrev_b64 v[2:3], 12, v[2:3]
	v_ashrrev_i32_e32 v5, 31, v4
	v_lshl_add_u64 v[2:3], v[0:1], 0, v[2:3]
	v_lshlrev_b64 v[4:5], 12, v[4:5]
	v_lshl_add_u64 v[0:1], v[0:1], 0, v[4:5]
	global_load_dwordx4 v[104:107], v[2:3], off
	global_load_dwordx4 v[108:111], v[0:1], off
